# v10_loop_heads_64B_aligned
# speedup vs baseline: 1.0531x; 1.0006x over previous
.LBB0_13:
	s_ashr_i32 s20, s31, 7
	s_ashr_i32 s21, s20, 31
	s_lshl_b32 s36, s31, 2
	s_lshl_b32 s33, s31, 6
	s_lshl_b64 s[34:35], s[20:21], 21
	s_add_u32 s37, s60, s34
	s_addc_u32 s35, s61, s35
	s_and_b32 s34, s36, 0x1e0
	s_lshl_b32 s36, s31, 8
	s_and_b32 s36, s36, 0x700
	v_or_b32_e32 v0, s34, v48
	s_add_u32 s36, s37, s36
	s_addc_u32 s37, s35, 0
	v_lshlrev_b32_e32 v50, 12, v0
	v_lshl_add_u64 v[54:55], s[36:37], 0, v[52:53]
	v_lshl_add_u64 v[56:57], s[6:7], 0, v[50:51]
	s_mov_b32 s35, 0
	v_mov_b32_e32 v0, 0
	v_mov_b32_e32 v1, v51
	v_mov_b32_e32 v2, v51
	v_mov_b32_e32 v3, v51
	v_mov_b32_e32 v4, 0
	v_mov_b32_e32 v5, v51
	v_mov_b32_e32 v6, v51
	v_mov_b32_e32 v7, v51
	v_mov_b32_e32 v8, 0
	v_mov_b32_e32 v9, v51
	v_mov_b32_e32 v10, v51
	v_mov_b32_e32 v11, v51
	v_mov_b32_e32 v12, 0
	v_mov_b32_e32 v13, v51
	v_mov_b32_e32 v14, v51
	v_mov_b32_e32 v15, v51
	v_mov_b32_e32 v16, 0
	v_mov_b32_e32 v17, v51
	v_mov_b32_e32 v18, v51
	v_mov_b32_e32 v19, v51
	v_mov_b32_e32 v20, 0
	v_mov_b32_e32 v21, v51
	v_mov_b32_e32 v22, v51
	v_mov_b32_e32 v23, v51
	v_mov_b32_e32 v24, 0
	v_mov_b32_e32 v25, v51
	v_mov_b32_e32 v26, v51
	v_mov_b32_e32 v27, v51
	v_mov_b32_e32 v28, 0
	v_mov_b32_e32 v29, v51
	v_mov_b32_e32 v30, v51
	v_mov_b32_e32 v31, v51
	.p2align	6

.LBB0_211:
	s_ashr_i32 s37, s36, 31
	s_lshl_b64 s[38:39], s[36:37], 19
	s_add_u32 s38, s55, s38
	s_addc_u32 s39, s56, s39
	s_and_b64 s[40:41], s[0:1], exec
	s_cselect_b32 s3, s39, s5
	s_cselect_b32 s37, s38, s4
	s_ashr_i32 s35, s34, 31
	s_lshl_b64 s[40:41], s[34:35], 19
	s_add_u32 s40, s57, s40
	s_addc_u32 s41, s58, s41
	s_and_b64 s[46:47], s[0:1], exec
	s_cselect_b32 s35, s41, s45
	s_cselect_b32 s79, s40, s44
	s_add_u32 s80, s44, 0x100
	v_mov_b32_e32 v0, 0
	s_addc_u32 s81, s45, 0
	s_mov_b32 s82, -2
	v_mov_b32_e32 v1, v0
	v_mov_b32_e32 v2, v0
	v_mov_b32_e32 v3, v0
	v_mov_b32_e32 v4, v0
	v_mov_b32_e32 v5, v0
	v_mov_b32_e32 v6, v0
	v_mov_b32_e32 v7, v0
	v_mov_b32_e32 v16, v0
	v_mov_b32_e32 v17, v0
	v_mov_b32_e32 v18, v0
	v_mov_b32_e32 v19, v0
	v_mov_b32_e32 v20, v0
	v_mov_b32_e32 v21, v0
	v_mov_b32_e32 v22, v0
	v_mov_b32_e32 v23, v0
	v_mov_b32_e32 v32, v0
	v_mov_b32_e32 v33, v0
	v_mov_b32_e32 v34, v0
	v_mov_b32_e32 v35, v0
	v_mov_b32_e32 v36, v0
	v_mov_b32_e32 v37, v0
	v_mov_b32_e32 v38, v0
	v_mov_b32_e32 v39, v0
	v_mov_b32_e32 v48, v0
	v_mov_b32_e32 v49, v0
	v_mov_b32_e32 v50, v0
	v_mov_b32_e32 v51, v0
	v_mov_b32_e32 v52, v0
	v_mov_b32_e32 v53, v0
	v_mov_b32_e32 v54, v0
	v_mov_b32_e32 v55, v0
	v_mov_b32_e32 v8, v0
	v_mov_b32_e32 v9, v0
	v_mov_b32_e32 v10, v0
	v_mov_b32_e32 v11, v0
	v_mov_b32_e32 v12, v0
	v_mov_b32_e32 v13, v0
	v_mov_b32_e32 v14, v0
	v_mov_b32_e32 v15, v0
	v_mov_b32_e32 v24, v0
	v_mov_b32_e32 v25, v0
	v_mov_b32_e32 v26, v0
	v_mov_b32_e32 v27, v0
	v_mov_b32_e32 v28, v0
	v_mov_b32_e32 v29, v0
	v_mov_b32_e32 v30, v0
	v_mov_b32_e32 v31, v0
	v_mov_b32_e32 v40, v0
	v_mov_b32_e32 v41, v0
	v_mov_b32_e32 v42, v0
	v_mov_b32_e32 v43, v0
	v_mov_b32_e32 v44, v0
	v_mov_b32_e32 v45, v0
	v_mov_b32_e32 v46, v0
	v_mov_b32_e32 v47, v0
	v_mov_b32_e32 v56, v0
	v_mov_b32_e32 v57, v0
	v_mov_b32_e32 v58, v0
	v_mov_b32_e32 v59, v0
	v_mov_b32_e32 v60, v0
	v_mov_b32_e32 v61, v0
	v_mov_b32_e32 v62, v0
	v_mov_b32_e32 v63, v0
	v_mov_b32_e32 v64, v0
	v_mov_b32_e32 v65, v0
	v_mov_b32_e32 v66, v0
	v_mov_b32_e32 v67, v0
	v_mov_b32_e32 v68, v0
	v_mov_b32_e32 v69, v0
	v_mov_b32_e32 v70, v0
	v_mov_b32_e32 v71, v0
	v_mov_b32_e32 v80, v0
	v_mov_b32_e32 v81, v0
	v_mov_b32_e32 v82, v0
	v_mov_b32_e32 v83, v0
	v_mov_b32_e32 v84, v0
	v_mov_b32_e32 v85, v0
	v_mov_b32_e32 v86, v0
	v_mov_b32_e32 v87, v0
	v_mov_b32_e32 v96, v0
	v_mov_b32_e32 v97, v0
	v_mov_b32_e32 v98, v0
	v_mov_b32_e32 v99, v0
	v_mov_b32_e32 v100, v0
	v_mov_b32_e32 v101, v0
	v_mov_b32_e32 v102, v0
	v_mov_b32_e32 v103, v0
	v_mov_b32_e32 v112, v0
	v_mov_b32_e32 v113, v0
	v_mov_b32_e32 v114, v0
	v_mov_b32_e32 v115, v0
	v_mov_b32_e32 v116, v0
	v_mov_b32_e32 v117, v0
	v_mov_b32_e32 v118, v0
	v_mov_b32_e32 v119, v0
	v_mov_b32_e32 v72, v0
	v_mov_b32_e32 v73, v0
	v_mov_b32_e32 v74, v0
	v_mov_b32_e32 v75, v0
	v_mov_b32_e32 v76, v0
	v_mov_b32_e32 v77, v0
	v_mov_b32_e32 v78, v0
	v_mov_b32_e32 v79, v0
	v_mov_b32_e32 v88, v0
	v_mov_b32_e32 v89, v0
	v_mov_b32_e32 v90, v0
	v_mov_b32_e32 v91, v0
	v_mov_b32_e32 v92, v0
	v_mov_b32_e32 v93, v0
	v_mov_b32_e32 v94, v0
	v_mov_b32_e32 v95, v0
	v_mov_b32_e32 v104, v0
	v_mov_b32_e32 v105, v0
	v_mov_b32_e32 v106, v0
	v_mov_b32_e32 v107, v0
	v_mov_b32_e32 v108, v0
	v_mov_b32_e32 v109, v0
	v_mov_b32_e32 v110, v0
	v_mov_b32_e32 v111, v0
	v_mov_b32_e32 v120, v0
	v_mov_b32_e32 v121, v0
	v_mov_b32_e32 v122, v0
	v_mov_b32_e32 v123, v0
	v_mov_b32_e32 v124, v0
	v_mov_b32_e32 v125, v0
	v_mov_b32_e32 v126, v0
	v_mov_b32_e32 v127, v0
	.p2align	6

.LBB0_421:
	s_add_i32 s74, s14, -2
	s_add_u32 s75, s26, 0x100
	s_addc_u32 s76, s27, 0
	s_add_u32 s77, s2, 0x100
	v_mov_b32_e32 v40, 0
	s_addc_u32 s78, s3, 0
	s_mov_b32 s2, 0
	v_mov_b32_e32 v41, v40
	v_mov_b32_e32 v42, v40
	v_mov_b32_e32 v43, v40
	v_mov_b32_e32 v48, v40
	v_mov_b32_e32 v49, v40
	v_mov_b32_e32 v50, v40
	v_mov_b32_e32 v51, v40
	v_mov_b32_e32 v64, v40
	v_mov_b32_e32 v65, v40
	v_mov_b32_e32 v66, v40
	v_mov_b32_e32 v67, v40
	v_mov_b32_e32 v68, v40
	v_mov_b32_e32 v69, v40
	v_mov_b32_e32 v70, v40
	v_mov_b32_e32 v71, v40
	v_mov_b32_e32 v80, v40
	v_mov_b32_e32 v81, v40
	v_mov_b32_e32 v82, v40
	v_mov_b32_e32 v83, v40
	v_mov_b32_e32 v84, v40
	v_mov_b32_e32 v85, v40
	v_mov_b32_e32 v86, v40
	v_mov_b32_e32 v87, v40
	v_mov_b32_e32 v88, v40
	v_mov_b32_e32 v89, v40
	v_mov_b32_e32 v90, v40
	v_mov_b32_e32 v91, v40
	v_mov_b32_e32 v92, v40
	v_mov_b32_e32 v93, v40
	v_mov_b32_e32 v94, v40
	v_mov_b32_e32 v95, v40
	v_mov_b32_e32 v0, v40
	v_mov_b32_e32 v1, v40
	v_mov_b32_e32 v2, v40
	v_mov_b32_e32 v3, v40
	v_mov_b32_e32 v4, v40
	v_mov_b32_e32 v5, v40
	v_mov_b32_e32 v6, v40
	v_mov_b32_e32 v7, v40
	v_mov_b32_e32 v8, v40
	v_mov_b32_e32 v9, v40
	v_mov_b32_e32 v10, v40
	v_mov_b32_e32 v11, v40
	v_mov_b32_e32 v12, v40
	v_mov_b32_e32 v13, v40
	v_mov_b32_e32 v14, v40
	v_mov_b32_e32 v15, v40
	v_mov_b32_e32 v16, v40
	v_mov_b32_e32 v17, v40
	v_mov_b32_e32 v18, v40
	v_mov_b32_e32 v19, v40
	v_mov_b32_e32 v20, v40
	v_mov_b32_e32 v21, v40
	v_mov_b32_e32 v22, v40
	v_mov_b32_e32 v23, v40
	v_mov_b32_e32 v24, v40
	v_mov_b32_e32 v25, v40
	v_mov_b32_e32 v26, v40
	v_mov_b32_e32 v27, v40
	v_mov_b32_e32 v28, v40
	v_mov_b32_e32 v29, v40
	v_mov_b32_e32 v30, v40
	v_mov_b32_e32 v31, v40
	v_mov_b32_e32 v96, v40
	v_mov_b32_e32 v97, v40
	v_mov_b32_e32 v98, v40
	v_mov_b32_e32 v99, v40
	v_mov_b32_e32 v100, v40
	v_mov_b32_e32 v101, v40
	v_mov_b32_e32 v102, v40
	v_mov_b32_e32 v103, v40
	v_mov_b32_e32 v104, v40
	v_mov_b32_e32 v105, v40
	v_mov_b32_e32 v106, v40
	v_mov_b32_e32 v107, v40
	v_mov_b32_e32 v108, v40
	v_mov_b32_e32 v109, v40
	v_mov_b32_e32 v110, v40
	v_mov_b32_e32 v111, v40
	v_mov_b32_e32 v112, v40
	v_mov_b32_e32 v113, v40
	v_mov_b32_e32 v114, v40
	v_mov_b32_e32 v115, v40
	v_mov_b32_e32 v116, v40
	v_mov_b32_e32 v117, v40
	v_mov_b32_e32 v118, v40
	v_mov_b32_e32 v119, v40
	v_mov_b32_e32 v120, v40
	v_mov_b32_e32 v121, v40
	v_mov_b32_e32 v122, v40
	v_mov_b32_e32 v123, v40
	v_mov_b32_e32 v124, v40
	v_mov_b32_e32 v125, v40
	v_mov_b32_e32 v126, v40
	v_mov_b32_e32 v127, v40
	v_mov_b32_e32 v32, v40
	v_mov_b32_e32 v33, v40
	v_mov_b32_e32 v34, v40
	v_mov_b32_e32 v35, v40
	v_mov_b32_e32 v36, v40
	v_mov_b32_e32 v37, v40
	v_mov_b32_e32 v38, v40
	v_mov_b32_e32 v39, v40
	v_mov_b32_e32 v44, v40
	v_mov_b32_e32 v45, v40
	v_mov_b32_e32 v46, v40
	v_mov_b32_e32 v47, v40
	v_mov_b32_e32 v52, v40
	v_mov_b32_e32 v53, v40
	v_mov_b32_e32 v54, v40
	v_mov_b32_e32 v55, v40
	v_mov_b32_e32 v56, v40
	v_mov_b32_e32 v57, v40
	v_mov_b32_e32 v58, v40
	v_mov_b32_e32 v59, v40
	v_mov_b32_e32 v60, v40
	v_mov_b32_e32 v61, v40
	v_mov_b32_e32 v62, v40
	v_mov_b32_e32 v63, v40
	v_mov_b32_e32 v72, v40
	v_mov_b32_e32 v73, v40
	v_mov_b32_e32 v74, v40
	v_mov_b32_e32 v75, v40
	v_mov_b32_e32 v76, v40
	v_mov_b32_e32 v77, v40
	v_mov_b32_e32 v78, v40
	v_mov_b32_e32 v79, v40
	.p2align	6

.LBB0_569:
	s_or_b64 exec, exec, s[48:49]
	s_add_i32 s48, s81, 0x100
	s_lshr_b32 s80, s48, 6
	s_add_u32 s66, s8, 0x18000
	s_addc_u32 s67, s9, 0
	s_cmp_lg_u32 0, -1
	s_cselect_b32 s48, 0, 0
	s_add_i32 s48, s48, s73
	s_add_i32 s48, s48, 0xe000
	s_mov_b32 m0, s48
	s_nop 0
	global_load_lds_dwordx4 v185, s[66:67]
	ds_read_b128 v[80:83], v179 offset:12288
	ds_read_b128 v[136:139], v179 offset:12800
	ds_read_b128 v[140:143], v179 offset:14336
	v_exp_f32_e32 v48, v16
	v_exp_f32_e32 v49, v17
	v_exp_f32_e32 v50, v18
	v_exp_f32_e32 v51, v19
	v_exp_f32_e32 v52, v20
	v_exp_f32_e32 v53, v21
	v_exp_f32_e32 v54, v22
	v_exp_f32_e32 v55, v23
	v_exp_f32_e32 v56, v24
	v_exp_f32_e32 v57, v25
	v_exp_f32_e32 v58, v26
	v_exp_f32_e32 v59, v27
	v_exp_f32_e32 v60, v28
	v_exp_f32_e32 v61, v29
	v_exp_f32_e32 v62, v30
	v_exp_f32_e32 v63, v31
	v_exp_f32_e32 v32, v0
	v_exp_f32_e32 v33, v1
	v_exp_f32_e32 v34, v2
	v_exp_f32_e32 v35, v3
	v_exp_f32_e32 v36, v4
	v_exp_f32_e32 v37, v5
	v_exp_f32_e32 v38, v6
	v_exp_f32_e32 v39, v7
	v_exp_f32_e32 v40, v8
	v_exp_f32_e32 v41, v9
	v_exp_f32_e32 v42, v10
	v_exp_f32_e32 v43, v11
	v_exp_f32_e32 v44, v12
	v_exp_f32_e32 v45, v13
	v_exp_f32_e32 v46, v14
	v_exp_f32_e32 v47, v15
	s_mov_b32 s86, 0
	s_andn2_b64 vcc, exec, s[0:1]
	s_mov_b32 s0, 1
	s_cbranch_vccnz .LBB0_595
	s_add_u32 s68, s8, 0x48000
	s_addc_u32 s69, s9, 0
	s_add_u32 s48, s64, 0xb4000
	s_addc_u32 s49, s65, 0
	v_mov_b32_e32 v16, v153
	v_mov_b32_e32 v17, v153
	s_add_u32 s8, s46, 0x5000
	v_mov_b32_e32 v18, v153
	v_mov_b32_e32 v19, v153
	v_mov_b32_e32 v20, v153
	v_mov_b32_e32 v21, v153
	v_mov_b32_e32 v22, v153
	v_mov_b32_e32 v23, v153
	v_mov_b32_e32 v24, v153
	v_mov_b32_e32 v25, v153
	v_mov_b32_e32 v26, v153
	v_mov_b32_e32 v27, v153
	v_mov_b32_e32 v28, v153
	v_mov_b32_e32 v29, v153
	v_mov_b32_e32 v30, v153
	v_mov_b32_e32 v31, v153
	v_mov_b64_e32 v[0:1], v[16:17]
	s_addc_u32 s9, s47, 0
	s_mov_b32 s0, 0
	s_movk_i32 s83, 0x6000
	s_movk_i32 s82, 0x3000
	s_movk_i32 s86, 0x4000
	s_movk_i32 s79, 0x2000
	s_mov_b64 s[60:61], 0
	v_mov_b32_e32 v166, 0
	s_mov_b32 s87, 6
	v_mov_b64_e32 v[2:3], v[18:19]
	v_mov_b64_e32 v[4:5], v[20:21]
	v_mov_b64_e32 v[6:7], v[22:23]
	v_mov_b64_e32 v[8:9], v[24:25]
	v_mov_b64_e32 v[10:11], v[26:27]
	v_mov_b64_e32 v[12:13], v[28:29]
	v_mov_b64_e32 v[14:15], v[30:31]
	s_mov_b32 s84, 0
	.p2align	6

.LBB0_598:
	v_lshl_add_u32 v64, s0, 6, v149
	v_subrev_u32_e32 v167, s81, v64
	s_sub_i32 s81, 0, s80
	s_add_i32 s87, s0, 2
	s_mul_i32 s9, s0, 0x18000
	s_mul_hi_u32 s8, s0, 0x18000
	s_add_u32 s66, s66, s9
	s_addc_u32 s67, s67, s8
	s_mul_i32 s9, s0, 0x24000
	s_mul_hi_u32 s8, s0, 0x24000
	s_add_u32 s9, s64, s9
	s_addc_u32 s8, s65, s8
	s_mov_b32 s1, s53
	s_add_u32 s64, s9, 0x90000
	s_addc_u32 s65, s8, 0
	s_lshl_b64 s[0:1], s[0:1], 12
	s_add_u32 s0, s46, s0
	s_addc_u32 s1, s47, s1
	s_add_u32 s68, s0, 0x4000
	s_addc_u32 s69, s1, 0
	.p2align	6

.LBB0_758:
	s_ashr_i32 s17, s16, 31
	s_lshl_b64 s[18:19], s[16:17], 19
	s_add_u32 s18, s31, s18
	s_addc_u32 s19, s33, s19
	s_and_b64 s[20:21], s[2:3], exec
	s_cselect_b32 s17, s19, s13
	s_cselect_b32 s56, s18, s12
	s_ashr_i32 s15, s14, 31
	s_lshl_b64 s[20:21], s[14:15], 19
	s_add_u32 s20, s34, s20
	s_addc_u32 s21, s35, s21
	s_and_b64 s[22:23], s[2:3], exec
	s_cselect_b32 s15, s21, s11
	s_cselect_b32 s57, s20, s10
	s_mov_b32 s58, -2
	s_mov_b64 s[22:23], 0
	.p2align	6

.LBB0_890:
	s_ashr_i32 s21, s20, 31
	s_lshl_b64 s[22:23], s[20:21], 19
	s_add_u32 s22, s42, s22
	s_addc_u32 s23, s43, s23
	s_and_b64 s[24:25], s[0:1], exec
	s_cselect_b32 s21, s23, s31
	s_cselect_b32 s29, s22, s30
	s_ashr_i32 s19, s18, 31
	s_lshl_b64 s[24:25], s[18:19], 19
	s_add_u32 s24, s44, s24
	s_addc_u32 s25, s45, s25
	s_and_b64 s[36:37], s[0:1], exec
	s_cselect_b32 s19, s25, s35
	s_cselect_b32 s68, s24, s34
	s_add_u32 s69, s34, 0x100
	v_mov_b32_e32 v0, 0
	s_addc_u32 s70, s35, 0
	s_mov_b32 s71, -2
	v_mov_b32_e32 v1, v0
	v_mov_b32_e32 v2, v0
	v_mov_b32_e32 v3, v0
	v_mov_b32_e32 v4, v0
	v_mov_b32_e32 v5, v0
	v_mov_b32_e32 v6, v0
	v_mov_b32_e32 v7, v0
	v_mov_b32_e32 v8, v0
	v_mov_b32_e32 v9, v0
	v_mov_b32_e32 v10, v0
	v_mov_b32_e32 v11, v0
	v_mov_b32_e32 v16, v0
	v_mov_b32_e32 v17, v0
	v_mov_b32_e32 v18, v0
	v_mov_b32_e32 v19, v0
	v_mov_b32_e32 v24, v0
	v_mov_b32_e32 v25, v0
	v_mov_b32_e32 v26, v0
	v_mov_b32_e32 v27, v0
	v_mov_b32_e32 v32, v0
	v_mov_b32_e32 v33, v0
	v_mov_b32_e32 v34, v0
	v_mov_b32_e32 v35, v0
	v_mov_b32_e32 v40, v0
	v_mov_b32_e32 v41, v0
	v_mov_b32_e32 v42, v0
	v_mov_b32_e32 v43, v0
	v_mov_b32_e32 v48, v0
	v_mov_b32_e32 v49, v0
	v_mov_b32_e32 v50, v0
	v_mov_b32_e32 v51, v0
	v_mov_b32_e32 v12, v0
	v_mov_b32_e32 v13, v0
	v_mov_b32_e32 v14, v0
	v_mov_b32_e32 v15, v0
	v_mov_b32_e32 v20, v0
	v_mov_b32_e32 v21, v0
	v_mov_b32_e32 v22, v0
	v_mov_b32_e32 v23, v0
	v_mov_b32_e32 v28, v0
	v_mov_b32_e32 v29, v0
	v_mov_b32_e32 v30, v0
	v_mov_b32_e32 v31, v0
	v_mov_b32_e32 v36, v0
	v_mov_b32_e32 v37, v0
	v_mov_b32_e32 v38, v0
	v_mov_b32_e32 v39, v0
	v_mov_b32_e32 v44, v0
	v_mov_b32_e32 v45, v0
	v_mov_b32_e32 v46, v0
	v_mov_b32_e32 v47, v0
	v_mov_b32_e32 v52, v0
	v_mov_b32_e32 v53, v0
	v_mov_b32_e32 v54, v0
	v_mov_b32_e32 v55, v0
	v_mov_b32_e32 v56, v0
	v_mov_b32_e32 v57, v0
	v_mov_b32_e32 v58, v0
	v_mov_b32_e32 v59, v0
	v_mov_b32_e32 v60, v0
	v_mov_b32_e32 v61, v0
	v_mov_b32_e32 v62, v0
	v_mov_b32_e32 v63, v0
	v_mov_b32_e32 v64, v0
	v_mov_b32_e32 v65, v0
	v_mov_b32_e32 v66, v0
	v_mov_b32_e32 v67, v0
	v_mov_b32_e32 v68, v0
	v_mov_b32_e32 v69, v0
	v_mov_b32_e32 v70, v0
	v_mov_b32_e32 v71, v0
	v_mov_b32_e32 v72, v0
	v_mov_b32_e32 v73, v0
	v_mov_b32_e32 v74, v0
	v_mov_b32_e32 v75, v0
	v_mov_b32_e32 v80, v0
	v_mov_b32_e32 v81, v0
	v_mov_b32_e32 v82, v0
	v_mov_b32_e32 v83, v0
	v_mov_b32_e32 v88, v0
	v_mov_b32_e32 v89, v0
	v_mov_b32_e32 v90, v0
	v_mov_b32_e32 v91, v0
	v_mov_b32_e32 v96, v0
	v_mov_b32_e32 v97, v0
	v_mov_b32_e32 v98, v0
	v_mov_b32_e32 v99, v0
	v_mov_b32_e32 v104, v0
	v_mov_b32_e32 v105, v0
	v_mov_b32_e32 v106, v0
	v_mov_b32_e32 v107, v0
	v_mov_b32_e32 v112, v0
	v_mov_b32_e32 v113, v0
	v_mov_b32_e32 v114, v0
	v_mov_b32_e32 v115, v0
	v_mov_b32_e32 v76, v0
	v_mov_b32_e32 v77, v0
	v_mov_b32_e32 v78, v0
	v_mov_b32_e32 v79, v0
	v_mov_b32_e32 v84, v0
	v_mov_b32_e32 v85, v0
	v_mov_b32_e32 v86, v0
	v_mov_b32_e32 v87, v0
	v_mov_b32_e32 v92, v0
	v_mov_b32_e32 v93, v0
	v_mov_b32_e32 v94, v0
	v_mov_b32_e32 v95, v0
	v_mov_b32_e32 v100, v0
	v_mov_b32_e32 v101, v0
	v_mov_b32_e32 v102, v0
	v_mov_b32_e32 v103, v0
	v_mov_b32_e32 v108, v0
	v_mov_b32_e32 v109, v0
	v_mov_b32_e32 v110, v0
	v_mov_b32_e32 v111, v0
	v_mov_b32_e32 v116, v0
	v_mov_b32_e32 v117, v0
	v_mov_b32_e32 v118, v0
	v_mov_b32_e32 v119, v0
	v_mov_b32_e32 v120, v0
	v_mov_b32_e32 v121, v0
	v_mov_b32_e32 v122, v0
	v_mov_b32_e32 v123, v0
	v_mov_b32_e32 v124, v0
	v_mov_b32_e32 v125, v0
	v_mov_b32_e32 v126, v0
	v_mov_b32_e32 v127, v0
	.p2align	6

.LBB0_1010:
	s_or_b64 exec, exec, s[0:1]
	s_movk_i32 s0, 0x110
	v_mov_b32_e32 v65, s33
	v_mad_u32_u24 v65, v101, s0, v65
	s_movk_i32 s0, 0xfef4
	v_mad_i32_i24 v67, v101, s0, v65
	s_movk_i32 s0, 0x440
	v_mul_lo_u32 v68, v103, s0
	s_movk_i32 s0, 0x90
	v_mov_b32_e32 v69, s70
	v_and_b32_e32 v64, -16, v184
	v_lshlrev_b32_e32 v66, 5, v103
	v_lshl_add_u32 v125, v118, 2, s33
	v_mad_u32_u24 v69, v101, s0, v69
	v_mov_b32_e32 v118, 1.0
	v_mov_b32_e32 v128, 0
	v_add3_u32 v142, v69, v64, 0
	s_movk_i32 s0, 0x1600
	v_add_u32_e32 v143, v65, v66
	v_add_u32_e32 v145, v67, v68
	v_mov_b32_e32 v122, 0
	v_mov_b32_e32 v123, v128
	v_mov_b32_e32 v120, 0
	v_mov_b32_e32 v121, v128
	v_mov_b32_e32 v119, v118
	v_mov_b32_e32 v126, v118
	v_mov_b32_e32 v127, v118
	.p2align	6

.LBB0_1060:
	s_or_b64 exec, exec, s[28:29]
	s_mov_b64 s[28:29], 0x1800
	s_mov_b64 s[52:53], 0x2400
	s_mov_b64 s[54:55], 0x1000
	s_mov_b64 s[56:57], 0x1040
	s_mov_b64 s[30:31], 0x1840
	s_mov_b64 s[34:35], 0x2000
	s_mov_b64 s[36:37], 0x2040
	s_mov_b64 s[38:39], 0x2800
	s_mov_b64 s[40:41], 0x2840
	s_mov_b64 s[42:43], 0x3000
	s_mov_b64 s[44:45], 0x3040
	s_mov_b64 s[46:47], 0x3800
	s_mov_b64 s[48:49], 0x3840
	s_and_saveexec_b64 s[58:59], s[16:17]
	s_movk_i32 s60, 0x90
	v_mad_u64_u32 v[64:65], s[60:61], v122, s60, v[124:125]
	ds_write_b128 v64, v[96:99] offset:5632
	s_or_b64 exec, exec, s[58:59]
	v_lshl_add_u64 v[168:169], v[126:127], 0, s[28:29]
	v_lshl_add_u64 v[148:149], v[142:143], 0, s[28:29]
	s_movk_i32 s28, 0x110
	v_mov_b32_e32 v65, s33
	v_mad_u32_u24 v65, v102, s28, v65
	s_movk_i32 s28, 0xfef4
	v_mad_i32_i24 v67, v102, s28, v65
	s_movk_i32 s28, 0x440
	v_mul_lo_u32 v68, v103, s28
	s_movk_i32 s28, 0x90
	v_mov_b32_e32 v69, s70
	v_and_b32_e32 v64, -16, v184
	v_lshlrev_b32_e32 v66, 5, v103
	v_mad_u32_u24 v69, v102, s28, v69
	v_mov_b32_e32 v172, 1.0
	v_mov_b32_e32 v180, 0
	v_lshl_add_u64 v[170:171], v[126:127], 0, s[52:53]
	v_lshl_add_u64 v[144:145], v[142:143], 0, s[54:55]
	v_lshl_add_u64 v[146:147], v[142:143], 0, s[56:57]
	v_lshl_add_u64 v[150:151], v[142:143], 0, s[30:31]
	v_lshl_add_u64 v[152:153], v[142:143], 0, s[34:35]
	v_lshl_add_u64 v[154:155], v[142:143], 0, s[36:37]
	v_lshl_add_u64 v[156:157], v[142:143], 0, s[38:39]
	v_lshl_add_u64 v[158:159], v[142:143], 0, s[40:41]
	v_lshl_add_u64 v[160:161], v[142:143], 0, s[42:43]
	v_lshl_add_u64 v[162:163], v[142:143], 0, s[44:45]
	v_lshl_add_u64 v[164:165], v[142:143], 0, s[46:47]
	v_lshl_add_u64 v[166:167], v[142:143], 0, s[48:49]
	v_lshl_add_u32 v125, v100, 2, s33
	v_add3_u32 v185, v69, v64, 0
	s_movk_i32 s28, 0x1600
	v_add_u32_e32 v186, v65, v66
	v_add_u32_e32 v187, v67, v68
	v_mov_b32_e32 v174, 0
	v_mov_b32_e32 v175, v180
	v_mov_b32_e32 v178, 0
	v_mov_b32_e32 v182, 0
	v_mov_b32_e32 v173, v172
	v_mov_b32_e32 v176, v172
	v_mov_b32_e32 v177, v172
	.p2align	6

.LBB0_1094:
	s_or_b64 exec, exec, s[0:1]
	v_mov_b32_e32 v118, 1.0
	v_mov_b32_e32 v116, 0
	s_movk_i32 s0, 0x1600
	v_mov_b32_e32 v122, 0
	v_mov_b32_e32 v123, v116
	v_mov_b32_e32 v120, 0
	v_mov_b32_e32 v121, v116
	v_mov_b32_e32 v119, v118
	v_mov_b32_e32 v126, v118
	v_mov_b32_e32 v127, v118
	.p2align	6

.LBB0_1183:
	s_mov_b32 s79, s73
	s_or_b64 exec, exec, s[26:27]
	v_add_u32_e32 v0, s22, v182
	v_ashrrev_i32_e32 v1, 31, v0
	v_readlane_b32 s36, v246, 2
	v_lshlrev_b64 v[0:1], 2, v[0:1]
	v_readlane_b32 s38, v246, 4
	v_readlane_b32 s39, v246, 5
	v_readlane_b32 s40, v246, 6
	v_readlane_b32 s41, v246, 7
	v_lshl_add_u64 v[2:3], s[38:39], 0, v[0:1]
	v_add_co_u32_e32 v4, vcc, 0x1000, v2
	v_and_b32_e32 v103, 15, v182
	s_nop 0
	v_addc_co_u32_e32 v5, vcc, 0, v3, vcc
	v_add_co_u32_e32 v6, vcc, 0x2000, v2
	v_lshl_add_u64 v[0:1], s[40:41], 0, v[0:1]
	s_nop 0
	v_addc_co_u32_e32 v7, vcc, 0, v3, vcc
	global_load_dword v68, v[2:3], off
	global_load_dword v109, v[2:3], off offset:3072
	global_load_dword v111, v[4:5], off offset:2048
	global_load_dword v113, v[6:7], off offset:1024
	global_load_dword v115, v[0:1], off
	v_or_b32_e32 v0, s22, v103
	v_ashrrev_i32_e32 v1, 31, v0
	v_readlane_b32 s44, v246, 10
	v_readlane_b32 s45, v246, 11
	v_lshlrev_b64 v[2:3], 2, v[0:1]
	v_readlane_b32 s48, v246, 14
	v_readlane_b32 s49, v246, 15
	v_lshl_add_u64 v[4:5], s[44:45], 0, v[2:3]
	v_or_b32_e32 v8, 16, v0
	v_lshl_add_u64 v[6:7], s[48:49], 0, v[2:3]
	global_load_dword v133, v[4:5], off
	global_load_dword v134, v[4:5], off offset:64
	global_load_dword v135, v[4:5], off offset:128
	global_load_dword v136, v[4:5], off offset:192
	global_load_dword v137, v[6:7], off
	global_load_dword v138, v[6:7], off offset:64
	global_load_dword v139, v[6:7], off offset:128
	global_load_dword v140, v[6:7], off offset:192
	v_or_b32_e32 v10, 32, v0
	v_or_b32_e32 v0, 48, v0
	v_lshl_add_u64 v[2:3], s[62:63], 0, v[2:3]
	v_ashrrev_i32_e32 v9, 31, v8
	v_ashrrev_i32_e32 v11, 31, v10
	v_ashrrev_i32_e32 v1, 31, v0
	v_lshl_add_u64 v[8:9], v[8:9], 2, s[62:63]
	v_lshl_add_u64 v[10:11], v[10:11], 2, s[62:63]
	v_lshl_add_u64 v[0:1], v[0:1], 2, s[62:63]
	global_load_dword v141, v[2:3], off
	global_load_dword v142, v[8:9], off
	global_load_dword v143, v[10:11], off
	global_load_dword v144, v[0:1], off
	v_ashrrev_i32_e32 v107, 4, v182
	s_mov_b32 s65, 0
	s_cmp_lt_i32 s18, 1
	v_lshlrev_b32_e32 v105, 5, v107
	v_readlane_b32 s37, v246, 3
	v_readlane_b32 s42, v246, 8
	v_readlane_b32 s43, v246, 9
	v_readlane_b32 s46, v246, 12
	v_readlane_b32 s47, v246, 13
	v_readlane_b32 s50, v246, 16
	v_readlane_b32 s51, v246, 17
	s_cbranch_scc1 .LBB0_1186
	v_sub_u32_e32 v0, s18, v105
	v_med3_i32 v2, v0, 0, 32
	v_lshl_add_u32 v3, s20, 7, v105
	s_movk_i32 s19, 0x300
	v_mov_b64_e32 v[0:1], s[22:23]
	v_mad_i64_i32 v[0:1], s[20:21], v3, s19, v[0:1]
	v_or_b32_e32 v0, v0, v103
	v_lshl_add_u64 v[0:1], v[0:1], 3, s[60:61]
	s_min_i32 s72, s18, 32
	v_mov_b32_e32 v124, 1.0
	v_mov_b32_e32 v121, 0
	s_movk_i32 s73, 0x1800
	v_mov_b32_e32 v118, 0
	v_mov_b32_e32 v119, 0
	v_mov_b32_e32 v129, 0
	v_mov_b32_e32 v125, 1.0
	v_mov_b32_e32 v128, 1.0
	v_mov_b32_e32 v131, 1.0
	.p2align	6

.LBB0_1197:
	s_or_b64 exec, exec, s[0:1]
	s_movk_i32 s2, 0x440
	s_movk_i32 s0, 0x110
	v_mov_b32_e32 v64, s33
	v_mul_lo_u32 v69, v107, s2
	s_add_u32 s2, s52, s56
	v_mad_u32_u24 v67, v103, s0, v64
	v_and_b32_e32 v64, 16, v182
	s_addc_u32 s3, s53, s57
	v_cmp_eq_u32_e32 vcc, 0, v64
	v_lshl_add_u64 v[64:65], v[122:123], 1, s[2:3]
	s_mov_b64 s[2:3], 0xb000000
	v_lshl_add_u32 v132, v122, 2, s33
	v_lshl_add_u64 v[122:123], v[64:65], 0, s[2:3]
	s_mov_b64 s[2:3], 0xd800000
	v_pk_fma_f32 v[120:121], v[124:125], v[120:121], v[126:127]
	v_lshl_add_u64 v[124:125], v[64:65], 0, s[2:3]
	s_movk_i32 s2, 0x90
	v_mov_b32_e32 v64, s70
	v_and_b32_e32 v66, -16, v182
	s_movk_i32 s0, 0xfef4
	v_mad_u32_u24 v64, v103, s2, v64
	v_mad_i32_i24 v68, v103, s0, v67
	v_add3_u32 v145, v64, v66, 0
	v_lshl_or_b32 v64, s69, 6, v103
	s_lshl_b32 s2, s71, 13
	v_pk_fma_f32 v[118:119], v[128:129], v[118:119], v[130:131]
	v_cmp_gt_u32_e64 s[0:1], 2, v107
	v_subrev_u32_e32 v126, s2, v64
	s_movk_i32 s2, 0x1600
	v_add_u32_e32 v147, v67, v105
	v_add_u32_e32 v148, v68, v69
	v_mov_b32_e32 v128, 0
	.p2align	6

.LBB0_1242:
	s_or_b64 exec, exec, s[22:23]
	v_add_u32_e32 v0, s6, v182
	v_ashrrev_i32_e32 v1, 31, v0
	v_readlane_b32 s36, v246, 2
	v_lshlrev_b64 v[0:1], 2, v[0:1]
	v_readlane_b32 s38, v246, 4
	v_readlane_b32 s39, v246, 5
	v_and_b32_e32 v192, 15, v182
	v_readlane_b32 s40, v246, 6
	v_lshl_add_u64 v[120:121], s[38:39], 0, v[0:1]
	v_readlane_b32 s41, v246, 7
	v_add_co_u32_e32 v2, vcc, 0x1000, v120
	s_nop 0
	v_lshl_add_u64 v[128:129], s[40:41], 0, v[0:1]
	v_addc_co_u32_e32 v3, vcc, 0, v121, vcc
	v_or_b32_e32 v0, s6, v192
	v_add_co_u32_e32 v4, vcc, 0x2000, v120
	v_ashrrev_i32_e32 v1, 31, v0
	v_readlane_b32 s44, v246, 10
	v_readlane_b32 s45, v246, 11
	global_load_dword v68, v[120:121], off
	global_load_dword v136, v[120:121], off offset:3072
	v_addc_co_u32_e32 v5, vcc, 0, v121, vcc
	global_load_dword v147, v[2:3], off offset:2048
	global_load_dword v148, v[4:5], off offset:1024
	v_lshlrev_b64 v[2:3], 2, v[0:1]
	v_readlane_b32 s48, v246, 14
	v_readlane_b32 s49, v246, 15
	v_lshl_add_u64 v[126:127], s[44:45], 0, v[2:3]
	global_load_dword v149, v[128:129], off
	v_lshl_add_u64 v[122:123], s[48:49], 0, v[2:3]
	v_lshl_add_u64 v[124:125], s[62:63], 0, v[2:3]
	v_or_b32_e32 v2, 16, v0
	global_load_dword v193, v[126:127], off
	global_load_dword v194, v[126:127], off offset:64
	global_load_dword v195, v[126:127], off offset:128
	global_load_dword v196, v[126:127], off offset:192
	global_load_dword v197, v[122:123], off
	global_load_dword v198, v[122:123], off offset:64
	global_load_dword v199, v[122:123], off offset:128
	global_load_dword v200, v[122:123], off offset:192
	v_ashrrev_i32_e32 v3, 31, v2
	s_waitcnt lgkmcnt(0)
	v_lshl_add_u64 v[130:131], v[2:3], 2, s[62:63]
	v_or_b32_e32 v2, 32, v0
	v_or_b32_e32 v0, 48, v0
	v_ashrrev_i32_e32 v3, 31, v2
	v_ashrrev_i32_e32 v1, 31, v0
	v_lshl_add_u64 v[132:133], v[2:3], 2, s[62:63]
	v_lshl_add_u64 v[134:135], v[0:1], 2, s[62:63]
	global_load_dword v201, v[124:125], off
	global_load_dword v202, v[130:131], off
	global_load_dword v203, v[132:133], off
	global_load_dword v204, v[134:135], off
	v_ashrrev_i32_e32 v184, 4, v182
	s_mov_b64 s[62:63], 0x1800
	s_mov_b32 s67, 0
	s_mov_b64 s[68:69], 0x2400
	s_cmp_lt_i32 s56, 1
	v_lshlrev_b32_e32 v183, 5, v184
	v_readlane_b32 s37, v246, 3
	v_readlane_b32 s42, v246, 8
	v_readlane_b32 s43, v246, 9
	v_readlane_b32 s46, v246, 12
	v_readlane_b32 s47, v246, 13
	v_readlane_b32 s50, v246, 16
	v_readlane_b32 s51, v246, 17
	s_cbranch_scc1 .LBB0_1246
	v_sub_u32_e32 v0, s56, v183
	v_med3_i32 v2, v0, 0, 32
	v_lshl_add_u32 v3, s64, 7, v183
	s_movk_i32 s8, 0x300
	v_mov_b64_e32 v[0:1], s[6:7]
	v_mad_i64_i32 v[0:1], s[6:7], v3, s8, v[0:1]
	v_or_b32_e32 v0, v0, v192
	s_mov_b32 s50, s73
	v_lshl_add_u64 v[0:1], v[0:1], 3, s[60:61]
	s_min_i32 s60, s56, 32
	v_mov_b32_e32 v157, 1.0
	v_mov_b32_e32 v153, 0
	s_movk_i32 s61, 0x1800
	v_mov_b32_e32 v152, 0
	v_mov_b32_e32 v151, 0
	v_mov_b32_e32 v150, 0
	v_mov_b32_e32 v156, 1.0
	v_mov_b32_e32 v155, 1.0
	v_mov_b32_e32 v154, 1.0
	.p2align	6

.LBB0_1263:
	s_or_b64 exec, exec, s[6:7]
	s_mov_b64 s[6:7], 0x1000
	s_mov_b64 s[8:9], 0x1040
	s_mov_b64 s[22:23], 0x1800
	s_mov_b64 s[24:25], 0x1840
	s_mov_b64 s[26:27], 0x2000
	s_mov_b64 s[28:29], 0x2040
	s_mov_b64 s[30:31], 0x2800
	s_mov_b64 s[34:35], 0x2840
	s_mov_b64 s[36:37], 0x3000
	s_mov_b64 s[38:39], 0x3040
	s_mov_b64 s[40:41], 0x3800
	s_mov_b64 s[42:43], 0x3840
	s_and_saveexec_b64 s[44:45], s[20:21]
	s_movk_i32 s46, 0x90
	v_mad_u64_u32 v[64:65], s[46:47], v118, s46, v[136:137]
	ds_write_b128 v64, v[96:99] offset:5632
	s_or_b64 exec, exec, s[44:45]
	v_lshl_add_u64 v[146:147], v[142:143], 0, s[6:7]
	s_movk_i32 s6, 0x110
	v_mov_b32_e32 v65, s33
	v_lshl_add_u64 v[150:151], v[142:143], 0, s[22:23]
	v_mad_u32_u24 v66, v192, s6, v65
	s_movk_i32 s6, 0xfef4
	v_and_b32_e32 v65, 16, v182
	s_movk_i32 s22, 0x440
	v_mad_i32_i24 v67, v192, s6, v66
	v_cmp_eq_u32_e64 s[6:7], 0, v65
	v_mul_lo_u32 v68, v184, s22
	s_movk_i32 s22, 0x90
	v_mov_b32_e32 v65, s70
	v_and_b32_e32 v64, -16, v182
	v_mad_u32_u24 v65, v192, s22, v65
	v_add3_u32 v64, v65, v64, 0
	v_add_u32_e32 v189, 0x1600, v64
	s_lshl_b64 s[22:23], s[64:65], 24
	v_add_u32_e32 v64, s72, v192
	v_lshl_add_u64 v[152:153], v[142:143], 0, s[24:25]
	v_ashrrev_i32_e32 v65, 31, v64
	s_add_u32 s24, s54, s22
	v_lshlrev_b64 v[64:65], 11, v[64:65]
	s_addc_u32 s25, s55, s23
	v_lshl_add_u32 v188, v144, 2, s33
	v_lshl_add_u64 v[64:65], s[24:25], 0, v[64:65]
	v_lshlrev_b64 v[144:145], 1, v[144:145]
	v_lshl_add_u64 v[64:65], v[64:65], 0, v[144:145]
	v_lshl_add_u64 v[148:149], v[142:143], 0, s[8:9]
	v_lshl_add_u64 v[154:155], v[142:143], 0, s[26:27]
	v_lshl_add_u64 v[156:157], v[142:143], 0, s[28:29]
	v_lshl_add_u64 v[158:159], v[142:143], 0, s[30:31]
	v_lshl_add_u64 v[160:161], v[142:143], 0, s[34:35]
	v_lshl_add_u64 v[162:163], v[142:143], 0, s[36:37]
	v_lshl_add_u64 v[164:165], v[142:143], 0, s[38:39]
	v_lshl_add_u64 v[166:167], v[142:143], 0, s[40:41]
	v_lshl_add_u64 v[168:169], v[142:143], 0, s[42:43]
	v_pk_fma_f32 v[176:177], v[178:179], v[176:177], v[180:181]
	v_pk_fma_f32 v[178:179], v[172:173], v[170:171], v[174:175]
	v_cmp_gt_u32_e64 s[8:9], 2, v184
	v_lshl_add_u64 v[88:89], s[52:53], 0, v[64:65]
	s_mov_b64 s[24:25], 0
	v_add_u32_e32 v190, v66, v183
	v_add_u32_e32 v191, v67, v68
	v_mov_b32_e32 v90, 0
	s_mov_b32 s26, 0xd800000
	v_mov_b32_e32 v137, v189
	.p2align	6

.LBB0_1295:
	s_or_b64 exec, exec, s[0:1]
	v_or_b32_e32 v64, s28, v192
	v_ashrrev_i32_e32 v65, 31, v64
	s_add_u32 s0, s54, s22
	v_lshlrev_b64 v[64:65], 11, v[64:65]
	s_addc_u32 s1, s55, s23
	v_lshl_add_u64 v[64:65], s[0:1], 0, v[64:65]
	v_lshl_add_u64 v[64:65], v[64:65], 0, v[144:145]
	v_lshl_add_u64 v[180:181], s[52:53], 0, v[64:65]
	s_mov_b64 s[2:3], 0
	v_mov_b32_e32 v182, 0
	s_mov_b32 s4, 0xd800000
	.p2align	6

.LBB0_1378:
	s_ashr_i32 s17, s16, 31
	s_lshl_b64 s[18:19], s[16:17], 19
	s_add_u32 s18, s31, s18
	s_addc_u32 s19, s33, s19
	s_and_b64 s[20:21], s[2:3], exec
	s_cselect_b32 s17, s19, s13
	s_cselect_b32 s55, s18, s12
	s_ashr_i32 s15, s14, 31
	s_lshl_b64 s[20:21], s[14:15], 19
	s_add_u32 s20, s34, s20
	s_addc_u32 s21, s35, s21
	s_and_b64 s[22:23], s[2:3], exec
	s_cselect_b32 s15, s21, s11
	s_cselect_b32 s56, s20, s10
	s_mov_b32 s57, -2
	s_mov_b64 s[22:23], 0
	.p2align	6
